# norm phases' preamble (norm10, norm6 x2): gain/shift table loads issued together (9 loads, counted vmcnt) instead of a 4-trip loop of two dependent round trips
# speedup vs baseline: 1.0166x; 1.0055x over previous
.LBB0_802:
	v_lshlrev_b32_e32 v0, 4, v4
	s_load_dwordx2 s[0:1], s[46:47], 0xf8
	s_waitcnt lgkmcnt(0)
	global_load_dwordx4 v[6:9], v0, s[0:1]
	s_mov_b64 s[16:17], s[14:15]
	global_load_dwordx4 v[10:13], v0, s[16:17]
	s_add_u32 s16, s16, 0x4000
	s_addc_u32 s17, s17, 0
	global_load_dwordx4 v[14:17], v0, s[16:17]
	s_add_u32 s16, s16, 0x4000
	s_addc_u32 s17, s17, 0
	global_load_dwordx4 v[18:21], v0, s[16:17]
	s_add_u32 s16, s16, 0x4000
	s_addc_u32 s17, s17, 0
	global_load_dwordx4 v[26:29], v0, s[16:17]
	s_mov_b64 s[16:17], s[12:13]
	global_load_dwordx4 v[30:33], v0, s[16:17]
	s_add_u32 s16, s16, 0x4000
	s_addc_u32 s17, s17, 0
	global_load_dwordx4 v[34:37], v0, s[16:17]
	s_add_u32 s16, s16, 0x4000
	s_addc_u32 s17, s17, 0
	global_load_dwordx4 v[38:41], v0, s[16:17]
	s_add_u32 s16, s16, 0x4000
	s_addc_u32 s17, s17, 0
	global_load_dwordx4 v[42:45], v0, s[16:17]
	s_waitcnt vmcnt(7)
	v_pk_add_f32 v[10:11], v[10:11], 1.0 op_sel_hi:[1,0]
	v_pk_add_f32 v[12:13], v[12:13], 1.0 op_sel_hi:[1,0]
	v_pk_mul_f32 v[10:11], v[6:7], v[10:11]
	v_pk_mul_f32 v[12:13], v[8:9], v[12:13]
	ds_write_b128 v0, v[10:13]
	s_waitcnt vmcnt(6)
	v_pk_add_f32 v[14:15], v[14:15], 1.0 op_sel_hi:[1,0]
	v_pk_add_f32 v[16:17], v[16:17], 1.0 op_sel_hi:[1,0]
	v_pk_mul_f32 v[14:15], v[6:7], v[14:15]
	v_pk_mul_f32 v[16:17], v[8:9], v[16:17]
	ds_write_b128 v0, v[14:17] offset:8192
	s_waitcnt vmcnt(5)
	v_pk_add_f32 v[18:19], v[18:19], 1.0 op_sel_hi:[1,0]
	v_pk_add_f32 v[20:21], v[20:21], 1.0 op_sel_hi:[1,0]
	v_pk_mul_f32 v[18:19], v[6:7], v[18:19]
	v_pk_mul_f32 v[20:21], v[8:9], v[20:21]
	ds_write_b128 v0, v[18:21] offset:16384
	s_waitcnt vmcnt(4)
	v_pk_add_f32 v[26:27], v[26:27], 1.0 op_sel_hi:[1,0]
	v_pk_add_f32 v[28:29], v[28:29], 1.0 op_sel_hi:[1,0]
	v_pk_mul_f32 v[26:27], v[6:7], v[26:27]
	v_pk_mul_f32 v[28:29], v[8:9], v[28:29]
	ds_write_b128 v0, v[26:29] offset:24576
	s_waitcnt vmcnt(3)
	ds_write_b128 v0, v[30:33] offset:32768
	s_waitcnt vmcnt(2)
	ds_write_b128 v0, v[34:37] offset:40960
	s_waitcnt vmcnt(1)
	ds_write_b128 v0, v[38:41] offset:49152
	s_waitcnt vmcnt(0)
	ds_write_b128 v0, v[42:45] offset:57344
	s_or_b64 exec, exec, s[16:17]
	s_add_u32 s12, s10, 0xde30000
	s_addc_u32 s13, s11, 0
	s_add_u32 s14, s10, 0xde32000
	s_addc_u32 s15, s11, 0
	s_mov_b64 s[16:17], 0
	v_mov_b32_e32 v3, v2
	v_mov_b32_e32 v5, v4
.LBB0_804:
	v_lshlrev_b32_e32 v0, 4, v4
	global_load_dwordx4 v[6:9], v0, s[26:27]
	s_mov_b64 s[16:17], s[14:15]
	global_load_dwordx4 v[10:13], v0, s[16:17]
	s_add_u32 s16, s16, 0xc000
	s_addc_u32 s17, s17, 0
	global_load_dwordx4 v[14:17], v0, s[16:17]
	s_add_u32 s16, s16, 0xc000
	s_addc_u32 s17, s17, 0
	global_load_dwordx4 v[18:21], v0, s[16:17]
	s_add_u32 s16, s16, 0xc000
	s_addc_u32 s17, s17, 0
	global_load_dwordx4 v[26:29], v0, s[16:17]
	s_mov_b64 s[16:17], s[12:13]
	global_load_dwordx4 v[30:33], v0, s[16:17]
	s_add_u32 s16, s16, 0xc000
	s_addc_u32 s17, s17, 0
	global_load_dwordx4 v[34:37], v0, s[16:17]
	s_add_u32 s16, s16, 0xc000
	s_addc_u32 s17, s17, 0
	global_load_dwordx4 v[38:41], v0, s[16:17]
	s_add_u32 s16, s16, 0xc000
	s_addc_u32 s17, s17, 0
	global_load_dwordx4 v[42:45], v0, s[16:17]
	v_add_u32_e32 v46, s28, v0
	v_add_u32_e32 v47, s29, v0
	s_waitcnt vmcnt(7)
	v_pk_add_f32 v[10:11], v[10:11], 1.0 op_sel_hi:[1,0]
	v_pk_add_f32 v[12:13], v[12:13], 1.0 op_sel_hi:[1,0]
	v_pk_mul_f32 v[10:11], v[6:7], v[10:11]
	v_pk_mul_f32 v[12:13], v[8:9], v[12:13]
	ds_write_b128 v46, v[10:13]
	s_waitcnt vmcnt(6)
	v_pk_add_f32 v[14:15], v[14:15], 1.0 op_sel_hi:[1,0]
	v_pk_add_f32 v[16:17], v[16:17], 1.0 op_sel_hi:[1,0]
	v_pk_mul_f32 v[14:15], v[6:7], v[14:15]
	v_pk_mul_f32 v[16:17], v[8:9], v[16:17]
	ds_write_b128 v46, v[14:17] offset:8192
	s_waitcnt vmcnt(5)
	v_pk_add_f32 v[18:19], v[18:19], 1.0 op_sel_hi:[1,0]
	v_pk_add_f32 v[20:21], v[20:21], 1.0 op_sel_hi:[1,0]
	v_pk_mul_f32 v[18:19], v[6:7], v[18:19]
	v_pk_mul_f32 v[20:21], v[8:9], v[20:21]
	ds_write_b128 v46, v[18:21] offset:16384
	s_waitcnt vmcnt(4)
	v_pk_add_f32 v[26:27], v[26:27], 1.0 op_sel_hi:[1,0]
	v_pk_add_f32 v[28:29], v[28:29], 1.0 op_sel_hi:[1,0]
	v_pk_mul_f32 v[26:27], v[6:7], v[26:27]
	v_pk_mul_f32 v[28:29], v[8:9], v[28:29]
	ds_write_b128 v46, v[26:29] offset:24576
	s_waitcnt vmcnt(3)
	ds_write_b128 v47, v[30:33]
	s_waitcnt vmcnt(2)
	ds_write_b128 v47, v[34:37] offset:8192
	s_waitcnt vmcnt(1)
	ds_write_b128 v47, v[38:41] offset:16384
	s_waitcnt vmcnt(0)
	ds_write_b128 v47, v[42:45] offset:24576

.LBB0_1083:
	v_lshlrev_b32_e32 v0, 4, v4
	global_load_dwordx4 v[6:9], v0, s[10:11]
	s_mov_b64 s[16:17], s[12:13]
	global_load_dwordx4 v[10:13], v0, s[16:17]
	s_add_u32 s16, s16, 0xc000
	s_addc_u32 s17, s17, 0
	global_load_dwordx4 v[14:17], v0, s[16:17]
	s_add_u32 s16, s16, 0xc000
	s_addc_u32 s17, s17, 0
	global_load_dwordx4 v[18:21], v0, s[16:17]
	s_add_u32 s16, s16, 0xc000
	s_addc_u32 s17, s17, 0
	global_load_dwordx4 v[26:29], v0, s[16:17]
	s_mov_b64 s[16:17], s[14:15]
	global_load_dwordx4 v[30:33], v0, s[16:17]
	s_add_u32 s16, s16, 0xc000
	s_addc_u32 s17, s17, 0
	global_load_dwordx4 v[34:37], v0, s[16:17]
	s_add_u32 s16, s16, 0xc000
	s_addc_u32 s17, s17, 0
	global_load_dwordx4 v[38:41], v0, s[16:17]
	s_add_u32 s16, s16, 0xc000
	s_addc_u32 s17, s17, 0
	global_load_dwordx4 v[42:45], v0, s[16:17]
	s_waitcnt vmcnt(7)
	v_pk_add_f32 v[10:11], v[10:11], 1.0 op_sel_hi:[1,0]
	v_pk_add_f32 v[12:13], v[12:13], 1.0 op_sel_hi:[1,0]
	v_pk_mul_f32 v[10:11], v[6:7], v[10:11]
	v_pk_mul_f32 v[12:13], v[8:9], v[12:13]
	ds_write_b128 v0, v[10:13]
	s_waitcnt vmcnt(6)
	v_pk_add_f32 v[14:15], v[14:15], 1.0 op_sel_hi:[1,0]
	v_pk_add_f32 v[16:17], v[16:17], 1.0 op_sel_hi:[1,0]
	v_pk_mul_f32 v[14:15], v[6:7], v[14:15]
	v_pk_mul_f32 v[16:17], v[8:9], v[16:17]
	ds_write_b128 v0, v[14:17] offset:8192
	s_waitcnt vmcnt(5)
	v_pk_add_f32 v[18:19], v[18:19], 1.0 op_sel_hi:[1,0]
	v_pk_add_f32 v[20:21], v[20:21], 1.0 op_sel_hi:[1,0]
	v_pk_mul_f32 v[18:19], v[6:7], v[18:19]
	v_pk_mul_f32 v[20:21], v[8:9], v[20:21]
	ds_write_b128 v0, v[18:21] offset:16384
	s_waitcnt vmcnt(4)
	v_pk_add_f32 v[26:27], v[26:27], 1.0 op_sel_hi:[1,0]
	v_pk_add_f32 v[28:29], v[28:29], 1.0 op_sel_hi:[1,0]
	v_pk_mul_f32 v[26:27], v[6:7], v[26:27]
	v_pk_mul_f32 v[28:29], v[8:9], v[28:29]
	ds_write_b128 v0, v[26:29] offset:24576
	s_waitcnt vmcnt(3)
	ds_write_b128 v0, v[30:33] offset:32768
	s_waitcnt vmcnt(2)
	ds_write_b128 v0, v[34:37] offset:40960
	s_waitcnt vmcnt(1)
	ds_write_b128 v0, v[38:41] offset:49152
	s_waitcnt vmcnt(0)
	ds_write_b128 v0, v[42:45] offset:57344
